# speedup vs baseline: 1.0063x; 1.0063x over previous
.LBB0_409:
	ds_read_b128 v[230:233], v191 offset:49152
	ds_read_b128 v[234:237], v191 offset:57344
	v_add_f32_e32 v174, 0, v162
	v_add_f32_e32 v174, v224, v174
	v_add_f32_e32 v174, v163, v174
	s_waitcnt lgkmcnt(1)
	v_mfma_f32_32x32x16_bf16 v[80:95], v[230:233], v[126:129], v[80:95]
	v_add_f32_e32 v174, v223, v174
	v_add_f32_e32 v174, v164, v174
	v_add_f32_e32 v174, v222, v174
	v_add_f32_e32 v174, v165, v174
	v_add_f32_e32 v174, v207, v174
	v_add_f32_e32 v174, v166, v174
	v_add_f32_e32 v174, v173, v174
	s_waitcnt lgkmcnt(0)
	v_mfma_f32_32x32x16_bf16 v[64:79], v[234:237], v[126:129], v[64:79]
	ds_read_b128 v[230:233], v192 offset:49152
	ds_read_b128 v[234:237], v192 offset:57344
	v_add_f32_e32 v174, v167, v174
	v_add_f32_e32 v174, v172, v174
	v_exp_f32_e32 v160, v160
	v_add_f32_e32 v174, v168, v174
	v_exp_f32_e32 v161, v161
	v_add_f32_e32 v174, v171, v174
	s_waitcnt lgkmcnt(1)
	v_mfma_f32_32x32x16_bf16 v[80:95], v[230:233], v[122:125], v[80:95]
	v_exp_f32_e32 v158, v158
	v_add_f32_e32 v174, v169, v174
	v_exp_f32_e32 v159, v159
	v_add_f32_e32 v174, v170, v174
	v_exp_f32_e32 v156, v156
	v_add_f32_e32 v174, v160, v174
	v_exp_f32_e32 v157, v157
	s_waitcnt lgkmcnt(0)
	v_mfma_f32_32x32x16_bf16 v[64:79], v[234:237], v[122:125], v[64:79]
	ds_read_b128 v[230:233], v193 offset:49152
	ds_read_b128 v[234:237], v193 offset:57344
	v_add_f32_e32 v174, v161, v174
	v_exp_f32_e32 v154, v154
	v_add_f32_e32 v174, v158, v174
	v_exp_f32_e32 v155, v155
	v_add_f32_e32 v174, v159, v174
	v_exp_f32_e32 v152, v152
	s_waitcnt lgkmcnt(1)
	v_mfma_f32_32x32x16_bf16 v[80:95], v[230:233], v[118:121], v[80:95]
	v_add_f32_e32 v174, v156, v174
	v_exp_f32_e32 v153, v153
	v_add_f32_e32 v174, v157, v174
	v_exp_f32_e32 v150, v150
	v_add_f32_e32 v174, v154, v174
	v_exp_f32_e32 v151, v151
	v_add_f32_e32 v174, v155, v174
	s_waitcnt lgkmcnt(0)
	v_mfma_f32_32x32x16_bf16 v[64:79], v[234:237], v[118:121], v[64:79]
	ds_read_b128 v[230:233], v194 offset:49152
	ds_read_b128 v[234:237], v194 offset:57344
	v_exp_f32_e32 v148, v148
	v_add_f32_e32 v174, v152, v174
	v_exp_f32_e32 v149, v149
	v_add_f32_e32 v174, v153, v174
	v_exp_f32_e32 v146, v146
	v_add_f32_e32 v174, v150, v174
	s_waitcnt lgkmcnt(1)
	v_mfma_f32_32x32x16_bf16 v[80:95], v[230:233], v[114:117], v[80:95]
	v_exp_f32_e32 v147, v147
	v_add_f32_e32 v174, v151, v174
	v_add_f32_e32 v174, v148, v174
	v_add_f32_e32 v174, v149, v174
	v_add_f32_e32 v174, v146, v174
	v_add_f32_e32 v225, v147, v174
	v_mov_b32_e32 v226, v225
	s_waitcnt lgkmcnt(0)
	v_mfma_f32_32x32x16_bf16 v[64:79], v[234:237], v[114:117], v[64:79]
	ds_read_b128 v[230:233], v195 offset:49152
	ds_read_b128 v[234:237], v195 offset:57344
	v_cvt_pk_bf16_f32 v162, v162, v224
	v_cvt_pk_bf16_f32 v164, v164, v222
	v_permlane32_swap_b32_e32 v225, v226
	v_cvt_pk_bf16_f32 v163, v163, v223
	v_cvt_pk_bf16_f32 v165, v165, v207
	s_waitcnt lgkmcnt(1)
	v_mfma_f32_32x32x16_bf16 v[80:95], v[230:233], v[110:113], v[80:95]
	v_permlane32_swap_b32_e32 v162, v164
	v_cvt_pk_bf16_f32 v166, v166, v173
	v_cvt_pk_bf16_f32 v167, v167, v172
	v_cvt_pk_bf16_f32 v168, v168, v171
	v_cvt_pk_bf16_f32 v169, v169, v170
	v_cvt_pk_bf16_f32 v170, v160, v161
	s_waitcnt lgkmcnt(0)
	v_mfma_f32_32x32x16_bf16 v[64:79], v[234:237], v[110:113], v[64:79]
	ds_read_b128 v[230:233], v196 offset:49152
	ds_read_b128 v[234:237], v196 offset:57344
	v_cvt_pk_bf16_f32 v171, v158, v159
	v_cvt_pk_bf16_f32 v172, v156, v157
	v_cvt_pk_bf16_f32 v173, v154, v155
	v_permlane32_swap_b32_e32 v163, v165
	v_permlane32_swap_b32_e32 v166, v168
	s_waitcnt lgkmcnt(1)
	v_mfma_f32_32x32x16_bf16 v[80:95], v[230:233], v[106:109], v[80:95]
	v_permlane32_swap_b32_e32 v167, v169
	v_permlane32_swap_b32_e32 v170, v172
	v_permlane32_swap_b32_e32 v171, v173
	s_waitcnt lgkmcnt(0)
	v_mfma_f32_32x32x16_bf16 v[64:79], v[234:237], v[106:109], v[64:79]
	ds_read_b128 v[230:233], v197 offset:49152
	ds_read_b128 v[234:237], v197 offset:57344
	s_waitcnt lgkmcnt(1)
	v_mfma_f32_32x32x16_bf16 v[80:95], v[230:233], v[102:105], v[80:95]
	s_waitcnt lgkmcnt(0)
	v_mfma_f32_32x32x16_bf16 v[64:79], v[234:237], v[102:105], v[64:79]
	ds_read_b128 v[230:233], v198 offset:49152
	ds_read_b128 v[234:237], v198 offset:57344
	s_waitcnt lgkmcnt(1)
	v_mfma_f32_32x32x16_bf16 v[80:95], v[230:233], v[98:101], v[80:95]
	v_cvt_pk_bf16_f32 v230, v152, v153
	v_cvt_pk_bf16_f32 v231, v150, v151
	v_cvt_pk_bf16_f32 v232, v148, v149
	v_cvt_pk_bf16_f32 v233, v146, v147
	s_nop 0
	v_permlane32_swap_b32_e32 v230, v232
	s_waitcnt lgkmcnt(0)
	v_mfma_f32_32x32x16_bf16 v[64:79], v[234:237], v[98:101], v[64:79]
	ds_read_b64_tr_b16 v[234:235], v184 offset:0
	ds_read_b64_tr_b16 v[236:237], v184 offset:0x800
	ds_read_b64_tr_b16 v[238:239], v184 offset:0x1000
	ds_read_b64_tr_b16 v[240:241], v184 offset:0x1800
	ds_read_b64_tr_b16 v[242:243], v184 offset:0x2000
	ds_read_b64_tr_b16 v[244:245], v184 offset:0x2800
	ds_read_b64_tr_b16 v[246:247], v184 offset:0x3000
	ds_read_b64_tr_b16 v[248:249], v184 offset:0x3800
	v_permlane32_swap_b32_e32 v231, v233
	s_add_u32 s10, s18, 3
	s_addc_u32 s11, s19, 0
	s_cmp_lt_u32 s10, s87
	s_cselect_b64 s[0:1], -1, 0
	s_and_b64 s[8:9], s[0:1], exec
	s_cselect_b32 s8, 0, s87
	s_cselect_b32 s9, s55, s51
	s_cselect_b32 s12, s54, s50
	s_sub_u32 s10, s10, s8
	s_subb_u32 s11, s11, 0
	s_and_b64 s[0:1], s[0:1], exec
	s_cselect_b32 s13, s86, 0x80
	s_cselect_b32 s14, s41, s47
	s_cselect_b32 s15, s40, s46
	s_lshl_b32 s56, s13, 6
	s_mul_i32 s0, s56, s11
	s_mul_hi_u32 s1, s56, s10
	s_add_i32 s1, s1, s0
	s_mul_i32 s0, s56, s10
	s_lshl_b64 s[0:1], s[0:1], 1
	s_add_u32 s0, s15, s0
	v_mul_lo_u32 v146, s13, v189
	s_addc_u32 s1, s14, s1
	v_or_b32_e32 v174, v146, v190
	v_lshl_add_u64 v[150:151], s[0:1], 0, v[174:175]
	v_lshl_add_u64 v[150:151], v[150:151], 0, s[56:57]
	global_load_dwordx4 v[146:149], v174, s[0:1]
	s_nop 0
	global_load_dwordx4 v[150:153], v[150:151], off
	s_lshl_b32 s0, s8, 14
	s_sub_u32 s0, 0, s0
	s_subb_u32 s1, 0, 0
	s_add_u32 s0, s12, s0
	s_addc_u32 s1, s9, s1
	v_lshl_add_u64 v[158:159], s[0:1], 0, v[180:181]
	v_add_co_u32_e32 v154, vcc, s75, v158
	s_nop 1
	v_addc_co_u32_e32 v155, vcc, -1, v159, vcc
	global_load_dwordx4 v[154:157], v[154:155], off
	s_nop 0
	global_load_dwordx4 v[158:161], v[158:159], off
	s_waitcnt lgkmcnt(0)
	s_nop 0
	v_mfma_f32_32x32x16_bf16 v[0:15], v[162:165], v[234:237], v[0:15]
	ds_read_b64_tr_b16 v[234:235], v184 offset:0x200
	ds_read_b64_tr_b16 v[236:237], v184 offset:0xa00
	v_mfma_f32_32x32x16_bf16 v[0:15], v[166:169], v[238:241], v[0:15]
	ds_read_b64_tr_b16 v[238:239], v184 offset:0x1200
	ds_read_b64_tr_b16 v[240:241], v184 offset:0x1a00
	v_mfma_f32_32x32x16_bf16 v[0:15], v[170:173], v[242:245], v[0:15]
	ds_read_b64_tr_b16 v[242:243], v184 offset:0x2200
	ds_read_b64_tr_b16 v[244:245], v184 offset:0x2a00
	v_mfma_f32_32x32x16_bf16 v[0:15], v[230:233], v[246:249], v[0:15]
	ds_read_b64_tr_b16 v[246:247], v184 offset:0x3200
	ds_read_b64_tr_b16 v[248:249], v184 offset:0x3a00
	s_waitcnt lgkmcnt(0)
	v_mfma_f32_32x32x16_bf16 v[48:63], v[162:165], v[234:237], v[48:63]
	ds_read_b64_tr_b16 v[234:235], v184 offset:0x400
	ds_read_b64_tr_b16 v[236:237], v184 offset:0xc00
	v_mfma_f32_32x32x16_bf16 v[48:63], v[166:169], v[238:241], v[48:63]
	ds_read_b64_tr_b16 v[238:239], v184 offset:0x1400
	ds_read_b64_tr_b16 v[240:241], v184 offset:0x1c00
	v_mfma_f32_32x32x16_bf16 v[48:63], v[170:173], v[242:245], v[48:63]
	ds_read_b64_tr_b16 v[242:243], v184 offset:0x2400
	ds_read_b64_tr_b16 v[244:245], v184 offset:0x2c00
	v_mfma_f32_32x32x16_bf16 v[48:63], v[230:233], v[246:249], v[48:63]
	ds_read_b64_tr_b16 v[246:247], v184 offset:0x3400
	ds_read_b64_tr_b16 v[248:249], v184 offset:0x3c00
	s_waitcnt lgkmcnt(0)
	v_mfma_f32_32x32x16_bf16 v[32:47], v[162:165], v[234:237], v[32:47]
	ds_read_b64_tr_b16 v[234:235], v184 offset:0x600
	ds_read_b64_tr_b16 v[236:237], v184 offset:0xe00
	v_mfma_f32_32x32x16_bf16 v[32:47], v[166:169], v[238:241], v[32:47]
	ds_read_b64_tr_b16 v[238:239], v184 offset:0x1600
	ds_read_b64_tr_b16 v[240:241], v184 offset:0x1e00
	v_mfma_f32_32x32x16_bf16 v[32:47], v[170:173], v[242:245], v[32:47]
	ds_read_b64_tr_b16 v[242:243], v184 offset:0x2600
	ds_read_b64_tr_b16 v[244:245], v184 offset:0x2e00
	v_mfma_f32_32x32x16_bf16 v[32:47], v[230:233], v[246:249], v[32:47]
	ds_read_b64_tr_b16 v[246:247], v184 offset:0x3600
	ds_read_b64_tr_b16 v[248:249], v184 offset:0x3e00
	s_waitcnt lgkmcnt(0)
	v_mfma_f32_32x32x16_bf16 v[16:31], v[162:165], v[234:237], v[16:31]
	v_max_f32_e32 v162, v81, v81
	v_max_f32_e32 v163, v80, v80
	v_max_f32_e32 v162, v163, v162
	v_max3_f32 v162, v162, v82, v83
	v_max3_f32 v162, v162, v84, v85
	v_max3_f32 v162, v162, v86, v87
	v_max3_f32 v162, v162, v88, v89
	v_max3_f32 v162, v162, v90, v91
	v_max3_f32 v162, v162, v92, v93
	v_mfma_f32_32x32x16_bf16 v[16:31], v[166:169], v[238:241], v[16:31]
	v_max3_f32 v162, v162, v94, v95
	v_max3_f32 v162, v162, v64, v65
	v_max3_f32 v162, v162, v66, v67
	v_max3_f32 v162, v162, v68, v69
	v_max3_f32 v162, v162, v70, v71
	v_max3_f32 v162, v162, v72, v73
	v_max3_f32 v162, v162, v74, v75
	v_max3_f32 v162, v162, v76, v77
	v_mfma_f32_32x32x16_bf16 v[16:31], v[170:173], v[242:245], v[16:31]
	v_max3_f32 v162, v162, v78, v79
	v_mov_b32_e32 v163, v162
	s_nop 1
	v_permlane32_swap_b32_e32 v162, v163
	v_max_f32_e32 v163, v163, v163
	v_max_f32_e32 v162, v162, v162
	v_max_f32_e32 v162, v162, v163
	v_sub_f32_e32 v163, v162, v204
	v_cmp_ge_f32_e32 vcc, s80, v163
	v_max_f32_e32 v163, v204, v204
	v_max_f32_e32 v162, v163, v162
	v_mfma_f32_32x32x16_bf16 v[16:31], v[230:233], v[246:249], v[16:31]
	v_sub_f32_e32 v163, v204, v162
	v_mul_f32_e32 v163, 0x3e0293ee, v163
	v_exp_f32_e32 v163, v163
	s_cmp_eq_u64 vcc, exec
	s_cselect_b64 s[8:9], -1, 0
	s_barrier
	s_waitcnt vmcnt(4)
	v_cndmask_b32_e64 v227, v163, 1.0, s[8:9]
	v_cmp_gt_f32_e32 vcc, 1.0, v227
	s_waitcnt vmcnt(7)
	ds_write_b128 v199, v[130:133]
	s_waitcnt vmcnt(6)
	ds_write_b128 v200, v[134:137]
	s_waitcnt vmcnt(5)
	ds_write_b128 v201, v[138:141] offset:32768
	s_waitcnt vmcnt(4)
	ds_write_b128 v202, v[142:145] offset:32768
	s_cbranch_vccz .LBB0_413
	s_and_saveexec_b64 s[0:1], s[6:7]
	ds_write_b32 v187, v227 offset:128
	s_or_b64 exec, exec, s[0:1]
	s_waitcnt lgkmcnt(0)
	v_add_u32_e32 v142, v182, v176
	ds_read_b128 v[130:133], v142 offset:224
	ds_read_b128 v[134:137], v142 offset:192
	ds_read_b128 v[138:141], v142 offset:160
	ds_read_b128 v[142:145], v142 offset:128
	s_waitcnt lgkmcnt(3)
	v_pk_mul_f32 v[12:13], v[12:13], v[130:131]
	s_waitcnt lgkmcnt(2)
	v_pk_mul_f32 v[8:9], v[8:9], v[134:135]
	s_waitcnt lgkmcnt(1)
	v_pk_mul_f32 v[4:5], v[4:5], v[138:139]
	v_pk_mul_f32 v[14:15], v[14:15], v[132:133]
	v_pk_mul_f32 v[10:11], v[10:11], v[136:137]
	v_pk_mul_f32 v[6:7], v[6:7], v[140:141]
	s_waitcnt lgkmcnt(0)
	v_pk_mul_f32 v[2:3], v[2:3], v[144:145]
	v_pk_mul_f32 v[0:1], v[0:1], v[142:143]
	v_pk_mul_f32 v[60:61], v[60:61], v[130:131]
	v_pk_mul_f32 v[56:57], v[56:57], v[134:135]
	v_pk_mul_f32 v[52:53], v[52:53], v[138:139]
	v_pk_mul_f32 v[62:63], v[62:63], v[132:133]
	v_pk_mul_f32 v[58:59], v[58:59], v[136:137]
	v_pk_mul_f32 v[54:55], v[54:55], v[140:141]
	v_pk_mul_f32 v[50:51], v[50:51], v[144:145]
	v_pk_mul_f32 v[48:49], v[48:49], v[142:143]
	v_pk_mul_f32 v[44:45], v[44:45], v[130:131]
	v_pk_mul_f32 v[40:41], v[40:41], v[134:135]
	v_pk_mul_f32 v[36:37], v[36:37], v[138:139]
	v_pk_mul_f32 v[46:47], v[46:47], v[132:133]
	v_pk_mul_f32 v[42:43], v[42:43], v[136:137]
	v_pk_mul_f32 v[38:39], v[38:39], v[140:141]
	v_pk_mul_f32 v[34:35], v[34:35], v[144:145]
	v_pk_mul_f32 v[32:33], v[32:33], v[142:143]
	v_pk_mul_f32 v[28:29], v[28:29], v[130:131]
	v_pk_mul_f32 v[24:25], v[24:25], v[134:135]
	v_pk_mul_f32 v[20:21], v[20:21], v[138:139]
	v_pk_mul_f32 v[30:31], v[30:31], v[132:133]
	v_pk_mul_f32 v[26:27], v[26:27], v[136:137]
	v_pk_mul_f32 v[22:23], v[22:23], v[140:141]
	v_pk_mul_f32 v[18:19], v[18:19], v[144:145]
	v_pk_mul_f32 v[16:17], v[16:17], v[142:143]

.LBB0_417:
	ds_read_b128 v[228:231], v191 offset:32768
	ds_read_b128 v[232:235], v191 offset:40960
	v_exp_f32_e32 v237, v162
	v_add_f32_e32 v162, 0, v143
	v_add_f32_e32 v162, v145, v162
	s_waitcnt lgkmcnt(1)
	v_mfma_f32_32x32x16_bf16 v[80:95], v[228:231], v[126:129], v[80:95]
	v_add_f32_e32 v162, v141, v162
	v_add_f32_e32 v162, v144, v162
	v_add_f32_e32 v162, v140, v162
	v_add_f32_e32 v162, v142, v162
	v_add_f32_e32 v162, v138, v162
	v_add_f32_e32 v162, v139, v162
	v_add_f32_e32 v162, v135, v162
	s_waitcnt lgkmcnt(0)
	v_mfma_f32_32x32x16_bf16 v[64:79], v[232:235], v[126:129], v[64:79]
	ds_read_b128 v[228:231], v192 offset:32768
	ds_read_b128 v[232:235], v192 offset:40960
	v_add_f32_e32 v162, v137, v162
	v_add_f32_e32 v162, v134, v162
	v_add_f32_e32 v162, v136, v162
	v_exp_f32_e32 v171, v171
	v_add_f32_e32 v162, v131, v162
	v_exp_f32_e32 v172, v172
	s_waitcnt lgkmcnt(1)
	v_mfma_f32_32x32x16_bf16 v[80:95], v[228:231], v[122:125], v[80:95]
	v_add_f32_e32 v162, v133, v162
	v_exp_f32_e32 v173, v173
	v_add_f32_e32 v162, v130, v162
	v_exp_f32_e32 v174, v174
	v_add_f32_e32 v162, v132, v162
	v_exp_f32_e32 v207, v207
	v_add_f32_e32 v162, v171, v162
	s_waitcnt lgkmcnt(0)
	v_mfma_f32_32x32x16_bf16 v[64:79], v[232:235], v[122:125], v[64:79]
	ds_read_b128 v[228:231], v193 offset:32768
	ds_read_b128 v[232:235], v193 offset:40960
	v_exp_f32_e32 v224, v164
	v_add_f32_e32 v162, v172, v162
	v_add_f32_e32 v162, v173, v162
	v_add_f32_e32 v162, v174, v162
	v_add_f32_e32 v162, v207, v162
	v_add_f32_e32 v162, v224, v162
	s_waitcnt lgkmcnt(1)
	v_mfma_f32_32x32x16_bf16 v[80:95], v[228:231], v[118:121], v[80:95]
	v_exp_f32_e32 v236, v163
	v_exp_f32_e32 v222, v222
	v_exp_f32_e32 v223, v223
	v_cvt_pk_bf16_f32 v164, v140, v142
	v_cvt_pk_bf16_f32 v163, v141, v144
	s_waitcnt lgkmcnt(0)
	v_mfma_f32_32x32x16_bf16 v[64:79], v[232:235], v[118:121], v[64:79]
	ds_read_b128 v[228:231], v194 offset:32768
	ds_read_b128 v[232:235], v194 offset:40960
	s_waitcnt lgkmcnt(1)
	v_mfma_f32_32x32x16_bf16 v[80:95], v[228:231], v[114:117], v[80:95]
	s_waitcnt lgkmcnt(0)
	v_mfma_f32_32x32x16_bf16 v[64:79], v[232:235], v[114:117], v[64:79]
	ds_read_b128 v[228:231], v195 offset:32768
	ds_read_b128 v[232:235], v195 offset:40960
	s_waitcnt lgkmcnt(1)
	v_mfma_f32_32x32x16_bf16 v[80:95], v[228:231], v[110:113], v[80:95]
	s_waitcnt lgkmcnt(0)
	v_mfma_f32_32x32x16_bf16 v[64:79], v[232:235], v[110:113], v[64:79]
	ds_read_b128 v[228:231], v196 offset:32768
	ds_read_b128 v[232:235], v196 offset:40960
	s_waitcnt lgkmcnt(1)
	v_mfma_f32_32x32x16_bf16 v[80:95], v[228:231], v[106:109], v[80:95]
	s_waitcnt lgkmcnt(0)
	v_mfma_f32_32x32x16_bf16 v[64:79], v[232:235], v[106:109], v[64:79]
	ds_read_b128 v[228:231], v197 offset:32768
	ds_read_b128 v[232:235], v197 offset:40960
	s_waitcnt lgkmcnt(1)
	v_mfma_f32_32x32x16_bf16 v[80:95], v[228:231], v[102:105], v[80:95]
	s_waitcnt lgkmcnt(0)
	v_mfma_f32_32x32x16_bf16 v[64:79], v[232:235], v[102:105], v[64:79]
	ds_read_b128 v[228:231], v198 offset:32768
	ds_read_b128 v[232:235], v198 offset:40960
	s_waitcnt lgkmcnt(1)
	v_mfma_f32_32x32x16_bf16 v[80:95], v[228:231], v[98:101], v[80:95]
	v_exp_f32_e32 v230, v165
	v_exp_f32_e32 v231, v166
	v_cvt_pk_bf16_f32 v165, v138, v139
	v_cvt_pk_bf16_f32 v166, v135, v137
	v_add_f32_e32 v162, v230, v162
	v_add_f32_e32 v162, v231, v162
	v_permlane32_swap_b32_e32 v163, v165
	s_waitcnt lgkmcnt(0)
	v_mfma_f32_32x32x16_bf16 v[64:79], v[232:235], v[98:101], v[64:79]
	v_exp_f32_e32 v232, v167
	v_exp_f32_e32 v233, v168
	v_exp_f32_e32 v234, v169
	v_exp_f32_e32 v235, v170
	v_add_f32_e32 v162, v232, v162
	v_add_f32_e32 v162, v233, v162
	v_add_f32_e32 v162, v234, v162
	v_add_f32_e32 v162, v235, v162
	v_add_f32_e32 v162, v236, v162
	v_add_f32_e32 v162, v222, v162
	v_add_f32_e32 v162, v223, v162
	v_add_f32_e32 v228, v237, v162
	v_mov_b32_e32 v229, v228
	v_cvt_pk_bf16_f32 v162, v143, v145
	s_nop 1
	v_permlane32_swap_b32_e32 v228, v229
	v_permlane32_swap_b32_e32 v162, v164
	v_cvt_pk_bf16_f32 v167, v134, v136
	v_cvt_pk_bf16_f32 v168, v131, v133
	v_cvt_pk_bf16_f32 v169, v130, v132
	v_cvt_pk_bf16_f32 v170, v171, v172
	v_cvt_pk_bf16_f32 v171, v173, v174
	v_cvt_pk_bf16_f32 v172, v207, v224
	v_cvt_pk_bf16_f32 v173, v230, v231
	v_cvt_pk_bf16_f32 v230, v232, v233
	v_cvt_pk_bf16_f32 v231, v234, v235
	v_cvt_pk_bf16_f32 v232, v236, v222
	v_cvt_pk_bf16_f32 v233, v223, v237
	ds_read_b64_tr_b16 v[234:235], v205 offset:0
	ds_read_b64_tr_b16 v[236:237], v205 offset:0x800
	ds_read_b64_tr_b16 v[238:239], v205 offset:0x1000
	ds_read_b64_tr_b16 v[240:241], v205 offset:0x1800
	ds_read_b64_tr_b16 v[242:243], v205 offset:0x2000
	ds_read_b64_tr_b16 v[244:245], v205 offset:0x2800
	ds_read_b64_tr_b16 v[246:247], v205 offset:0x3000
	ds_read_b64_tr_b16 v[248:249], v205 offset:0x3800
	s_nop 0
	v_permlane32_swap_b32_e32 v166, v168
	v_permlane32_swap_b32_e32 v167, v169
	v_permlane32_swap_b32_e32 v170, v172
	v_permlane32_swap_b32_e32 v171, v173
	v_permlane32_swap_b32_e32 v230, v232
	v_permlane32_swap_b32_e32 v231, v233
	s_add_i32 s0, s18, 4
	s_min_i32 s10, s0, s52
	s_cmp_lt_i32 s10, s87
	s_cselect_b64 s[0:1], -1, 0
	s_and_b64 s[8:9], s[0:1], exec
	s_cselect_b32 s8, 0, s87
	s_sub_i32 s8, s10, s8
	s_and_b64 s[10:11], s[0:1], exec
	s_cselect_b32 s12, s55, s51
	s_cselect_b32 s13, s54, s50
	s_ashr_i32 s9, s8, 31
	s_lshl_b64 s[10:11], s[8:9], 14
	s_add_u32 s10, s13, s10
	s_addc_u32 s11, s12, s11
	s_and_b64 s[0:1], s[0:1], exec
	s_cselect_b32 s9, s86, 0x80
	s_cselect_b32 s12, s41, s47
	s_cselect_b32 s13, s40, s46
	s_lshl_b32 s56, s9, 6
	s_mul_hi_i32 s1, s56, s8
	s_mul_i32 s0, s56, s8
	s_lshl_b64 s[0:1], s[0:1], 1
	s_add_u32 s0, s13, s0
	v_mul_lo_u32 v130, s9, v189
	s_addc_u32 s1, s12, s1
	v_or_b32_e32 v174, v130, v190
	v_lshl_add_u64 v[138:139], s[10:11], 0, v[178:179]
	v_lshl_add_u64 v[134:135], s[0:1], 0, v[174:175]
	v_add_co_u32_e32 v142, vcc, s73, v138
	v_lshl_add_u64 v[134:135], v[134:135], 0, s[56:57]
	s_nop 0
	v_addc_co_u32_e32 v143, vcc, 0, v139, vcc
	global_load_dwordx4 v[130:133], v174, s[0:1]
	s_nop 0
	global_load_dwordx4 v[134:137], v[134:135], off
	s_nop 0
	global_load_dwordx4 v[138:141], v[138:139], off
	s_nop 0
	global_load_dwordx4 v[142:145], v[142:143], off
	s_waitcnt lgkmcnt(0)
	s_nop 0
	v_mfma_f32_32x32x16_bf16 v[0:15], v[162:165], v[234:237], v[0:15]
	ds_read_b64_tr_b16 v[234:235], v205 offset:0x200
	ds_read_b64_tr_b16 v[236:237], v205 offset:0xa00
	v_mfma_f32_32x32x16_bf16 v[0:15], v[166:169], v[238:241], v[0:15]
	ds_read_b64_tr_b16 v[238:239], v205 offset:0x1200
	ds_read_b64_tr_b16 v[240:241], v205 offset:0x1a00
	v_mfma_f32_32x32x16_bf16 v[0:15], v[170:173], v[242:245], v[0:15]
	ds_read_b64_tr_b16 v[242:243], v205 offset:0x2200
	ds_read_b64_tr_b16 v[244:245], v205 offset:0x2a00
	v_mfma_f32_32x32x16_bf16 v[0:15], v[230:233], v[246:249], v[0:15]
	ds_read_b64_tr_b16 v[246:247], v205 offset:0x3200
	ds_read_b64_tr_b16 v[248:249], v205 offset:0x3a00
	s_waitcnt lgkmcnt(0)
	v_mfma_f32_32x32x16_bf16 v[48:63], v[162:165], v[234:237], v[48:63]
	ds_read_b64_tr_b16 v[234:235], v205 offset:0x400
	ds_read_b64_tr_b16 v[236:237], v205 offset:0xc00
	v_mfma_f32_32x32x16_bf16 v[48:63], v[166:169], v[238:241], v[48:63]
	ds_read_b64_tr_b16 v[238:239], v205 offset:0x1400
	ds_read_b64_tr_b16 v[240:241], v205 offset:0x1c00
	v_mfma_f32_32x32x16_bf16 v[48:63], v[170:173], v[242:245], v[48:63]
	ds_read_b64_tr_b16 v[242:243], v205 offset:0x2400
	ds_read_b64_tr_b16 v[244:245], v205 offset:0x2c00
	v_mfma_f32_32x32x16_bf16 v[48:63], v[230:233], v[246:249], v[48:63]
	ds_read_b64_tr_b16 v[246:247], v205 offset:0x3400
	ds_read_b64_tr_b16 v[248:249], v205 offset:0x3c00
	s_waitcnt lgkmcnt(0)
	v_mfma_f32_32x32x16_bf16 v[32:47], v[162:165], v[234:237], v[32:47]
	ds_read_b64_tr_b16 v[234:235], v205 offset:0x600
	ds_read_b64_tr_b16 v[236:237], v205 offset:0xe00
	v_mfma_f32_32x32x16_bf16 v[32:47], v[166:169], v[238:241], v[32:47]
	ds_read_b64_tr_b16 v[238:239], v205 offset:0x1600
	ds_read_b64_tr_b16 v[240:241], v205 offset:0x1e00
	v_mfma_f32_32x32x16_bf16 v[32:47], v[170:173], v[242:245], v[32:47]
	ds_read_b64_tr_b16 v[242:243], v205 offset:0x2600
	ds_read_b64_tr_b16 v[244:245], v205 offset:0x2e00
	v_mfma_f32_32x32x16_bf16 v[32:47], v[230:233], v[246:249], v[32:47]
	ds_read_b64_tr_b16 v[246:247], v205 offset:0x3600
	ds_read_b64_tr_b16 v[248:249], v205 offset:0x3e00
	s_waitcnt lgkmcnt(0)
	v_mfma_f32_32x32x16_bf16 v[16:31], v[162:165], v[234:237], v[16:31]
	v_max_f32_e32 v162, v81, v81
	v_max_f32_e32 v163, v80, v80
	v_max_f32_e32 v162, v163, v162
	v_max3_f32 v162, v162, v82, v83
	v_max3_f32 v162, v162, v84, v85
	v_max3_f32 v162, v162, v86, v87
	v_max3_f32 v162, v162, v88, v89
	v_max3_f32 v162, v162, v90, v91
	v_max3_f32 v162, v162, v92, v93
	v_mfma_f32_32x32x16_bf16 v[16:31], v[166:169], v[238:241], v[16:31]
	v_max3_f32 v162, v162, v94, v95
	v_max3_f32 v162, v162, v64, v65
	v_max3_f32 v162, v162, v66, v67
	v_max3_f32 v162, v162, v68, v69
	v_max3_f32 v162, v162, v70, v71
	v_max3_f32 v162, v162, v72, v73
	v_max3_f32 v162, v162, v74, v75
	v_max3_f32 v162, v162, v76, v77
	v_mfma_f32_32x32x16_bf16 v[16:31], v[170:173], v[242:245], v[16:31]
	v_max3_f32 v162, v162, v78, v79
	v_mov_b32_e32 v163, v162
	s_nop 1
	v_permlane32_swap_b32_e32 v162, v163
	v_max_f32_e32 v163, v163, v163
	v_max_f32_e32 v162, v162, v162
	v_max_f32_e32 v162, v162, v163
	v_sub_f32_e32 v163, v162, v204
	v_cmp_ge_f32_e32 vcc, s80, v163
	v_max_f32_e32 v163, v204, v204
	v_max_f32_e32 v162, v163, v162
	v_mfma_f32_32x32x16_bf16 v[16:31], v[230:233], v[246:249], v[16:31]
	v_sub_f32_e32 v163, v204, v162
	v_mul_f32_e32 v163, 0x3e0293ee, v163
	v_exp_f32_e32 v163, v163
	s_cmp_eq_u64 vcc, exec
	s_cselect_b64 s[8:9], -1, 0
	s_barrier
	s_waitcnt vmcnt(4)
	v_cndmask_b32_e64 v174, v163, 1.0, s[8:9]
	v_cmp_gt_f32_e32 vcc, 1.0, v174
	s_waitcnt vmcnt(7)
	ds_write_b128 v199, v[146:149] offset:16384
	s_waitcnt vmcnt(6)
	ds_write_b128 v200, v[150:153] offset:16384
	s_waitcnt vmcnt(5)
	ds_write_b128 v201, v[154:157] offset:49152
	s_waitcnt vmcnt(4)
	ds_write_b128 v202, v[158:161] offset:49152
	s_cbranch_vccz .LBB0_421
	s_and_saveexec_b64 s[0:1], s[6:7]
	ds_write_b32 v187, v174 offset:128
	s_or_b64 exec, exec, s[0:1]
	s_waitcnt lgkmcnt(0)
	v_add_u32_e32 v158, v182, v176
	ds_read_b128 v[146:149], v158 offset:224
	ds_read_b128 v[150:153], v158 offset:192
	ds_read_b128 v[154:157], v158 offset:128
	ds_read_b128 v[158:161], v158 offset:160
	s_waitcnt lgkmcnt(3)
	v_pk_mul_f32 v[14:15], v[14:15], v[148:149]
	v_pk_mul_f32 v[12:13], v[12:13], v[146:147]
	s_waitcnt lgkmcnt(2)
	v_pk_mul_f32 v[10:11], v[10:11], v[152:153]
	v_pk_mul_f32 v[8:9], v[8:9], v[150:151]
	s_waitcnt lgkmcnt(0)
	v_pk_mul_f32 v[6:7], v[6:7], v[160:161]
	v_pk_mul_f32 v[4:5], v[4:5], v[158:159]
	v_pk_mul_f32 v[2:3], v[2:3], v[156:157]
	v_pk_mul_f32 v[0:1], v[0:1], v[154:155]
	v_pk_mul_f32 v[62:63], v[62:63], v[148:149]
	v_pk_mul_f32 v[60:61], v[60:61], v[146:147]
	v_pk_mul_f32 v[58:59], v[58:59], v[152:153]
	v_pk_mul_f32 v[56:57], v[56:57], v[150:151]
	v_pk_mul_f32 v[54:55], v[54:55], v[160:161]
	v_pk_mul_f32 v[52:53], v[52:53], v[158:159]
	v_pk_mul_f32 v[50:51], v[50:51], v[156:157]
	v_pk_mul_f32 v[48:49], v[48:49], v[154:155]
	v_pk_mul_f32 v[46:47], v[46:47], v[148:149]
	v_pk_mul_f32 v[44:45], v[44:45], v[146:147]
	v_pk_mul_f32 v[42:43], v[42:43], v[152:153]
	v_pk_mul_f32 v[40:41], v[40:41], v[150:151]
	v_pk_mul_f32 v[38:39], v[38:39], v[160:161]
	v_pk_mul_f32 v[36:37], v[36:37], v[158:159]
	v_pk_mul_f32 v[34:35], v[34:35], v[156:157]
	v_pk_mul_f32 v[32:33], v[32:33], v[154:155]
	v_pk_mul_f32 v[30:31], v[30:31], v[148:149]
	v_pk_mul_f32 v[28:29], v[28:29], v[146:147]
	v_pk_mul_f32 v[26:27], v[26:27], v[152:153]
	v_pk_mul_f32 v[24:25], v[24:25], v[150:151]
	v_pk_mul_f32 v[22:23], v[22:23], v[160:161]
	v_pk_mul_f32 v[20:21], v[20:21], v[158:159]
	v_pk_mul_f32 v[18:19], v[18:19], v[156:157]
	v_pk_mul_f32 v[16:17], v[16:17], v[154:155]

.LBB0_438:
	ds_read_b128 v[64:67], v188 offset:49152
	ds_read_b128 v[68:71], v188 offset:57344
	ds_read_b128 v[224:227], v189 offset:49152
	ds_read_b128 v[228:231], v189 offset:57344
	v_add_f32_e32 v162, 0, v206
	v_add_f32_e32 v162, v222, v162
	s_waitcnt lgkmcnt(3)
	v_mfma_f32_32x32x16_bf16 v[80:95], v[64:67], v[126:129], 0
	v_add_f32_e32 v162, v163, v162
	v_add_f32_e32 v162, v207, v162
	v_add_f32_e32 v162, v164, v162
	v_add_f32_e32 v162, v205, v162
	v_add_f32_e32 v162, v165, v162
	v_add_f32_e32 v162, v204, v162
	v_add_f32_e32 v162, v166, v162
	s_waitcnt lgkmcnt(2)
	v_mfma_f32_32x32x16_bf16 v[64:79], v[68:71], v[126:129], 0
	v_add_f32_e32 v162, v203, v162
	v_add_f32_e32 v162, v167, v162
	v_add_f32_e32 v162, v173, v162
	v_exp_f32_e32 v160, v160
	v_add_f32_e32 v162, v168, v162
	v_exp_f32_e32 v161, v161
	v_add_f32_e32 v162, v172, v162
	s_waitcnt lgkmcnt(1)
	v_mfma_f32_32x32x16_bf16 v[80:95], v[224:227], v[122:125], v[80:95]
	v_exp_f32_e32 v158, v158
	v_add_f32_e32 v162, v169, v162
	v_exp_f32_e32 v159, v159
	v_add_f32_e32 v162, v171, v162
	v_exp_f32_e32 v156, v156
	v_add_f32_e32 v162, v160, v162
	v_exp_f32_e32 v157, v157
	s_waitcnt lgkmcnt(0)
	v_mfma_f32_32x32x16_bf16 v[64:79], v[228:231], v[122:125], v[64:79]
	ds_read_b128 v[224:227], v190 offset:49152
	ds_read_b128 v[228:231], v190 offset:57344
	v_add_f32_e32 v162, v161, v162
	v_exp_f32_e32 v154, v154
	v_add_f32_e32 v162, v158, v162
	v_exp_f32_e32 v155, v155
	v_add_f32_e32 v162, v159, v162
	v_exp_f32_e32 v152, v152
	s_waitcnt lgkmcnt(1)
	v_mfma_f32_32x32x16_bf16 v[80:95], v[224:227], v[118:121], v[80:95]
	v_add_f32_e32 v162, v156, v162
	v_exp_f32_e32 v153, v153
	v_add_f32_e32 v162, v157, v162
	v_exp_f32_e32 v150, v150
	v_add_f32_e32 v162, v154, v162
	v_exp_f32_e32 v151, v151
	v_add_f32_e32 v162, v155, v162
	s_waitcnt lgkmcnt(0)
	v_mfma_f32_32x32x16_bf16 v[64:79], v[228:231], v[118:121], v[64:79]
	ds_read_b128 v[224:227], v191 offset:49152
	ds_read_b128 v[228:231], v191 offset:57344
	v_exp_f32_e32 v148, v148
	v_add_f32_e32 v162, v152, v162
	v_exp_f32_e32 v149, v149
	v_add_f32_e32 v162, v153, v162
	v_exp_f32_e32 v146, v146
	v_add_f32_e32 v162, v150, v162
	s_waitcnt lgkmcnt(1)
	v_mfma_f32_32x32x16_bf16 v[80:95], v[224:227], v[114:117], v[80:95]
	v_exp_f32_e32 v147, v147
	v_add_f32_e32 v162, v151, v162
	v_add_f32_e32 v162, v148, v162
	v_add_f32_e32 v162, v149, v162
	v_add_f32_e32 v162, v146, v162
	v_add_f32_e32 v223, v147, v162
	v_cvt_pk_bf16_f32 v162, v206, v222
	s_waitcnt lgkmcnt(0)
	v_mfma_f32_32x32x16_bf16 v[64:79], v[228:231], v[114:117], v[64:79]
	ds_read_b128 v[224:227], v192 offset:49152
	ds_read_b128 v[228:231], v192 offset:57344
	v_cvt_pk_bf16_f32 v164, v164, v205
	v_cvt_pk_bf16_f32 v163, v163, v207
	v_cvt_pk_bf16_f32 v165, v165, v204
	v_cvt_pk_bf16_f32 v166, v166, v203
	v_cvt_pk_bf16_f32 v167, v167, v173
	v_cvt_pk_bf16_f32 v168, v168, v172
	s_waitcnt lgkmcnt(1)
	v_mfma_f32_32x32x16_bf16 v[80:95], v[224:227], v[110:113], v[80:95]
	v_permlane32_swap_b32_e32 v162, v164
	v_cvt_pk_bf16_f32 v169, v169, v171
	v_cvt_pk_bf16_f32 v204, v160, v161
	v_cvt_pk_bf16_f32 v205, v158, v159
	v_cvt_pk_bf16_f32 v206, v156, v157
	v_cvt_pk_bf16_f32 v207, v154, v155
	s_waitcnt lgkmcnt(0)
	v_mfma_f32_32x32x16_bf16 v[64:79], v[228:231], v[110:113], v[64:79]
	ds_read_b128 v[224:227], v193 offset:49152
	ds_read_b128 v[228:231], v193 offset:57344
	v_permlane32_swap_b32_e32 v163, v165
	v_permlane32_swap_b32_e32 v166, v168
	v_permlane32_swap_b32_e32 v167, v169
	s_waitcnt lgkmcnt(1)
	v_mfma_f32_32x32x16_bf16 v[80:95], v[224:227], v[106:109], v[80:95]
	v_permlane32_swap_b32_e32 v204, v206
	v_permlane32_swap_b32_e32 v205, v207
	s_waitcnt lgkmcnt(0)
	v_mfma_f32_32x32x16_bf16 v[64:79], v[228:231], v[106:109], v[64:79]
	ds_read_b128 v[224:227], v195 offset:49152
	ds_read_b128 v[228:231], v195 offset:57344
	s_waitcnt lgkmcnt(1)
	v_mfma_f32_32x32x16_bf16 v[80:95], v[224:227], v[102:105], v[80:95]
	s_waitcnt lgkmcnt(0)
	v_mfma_f32_32x32x16_bf16 v[64:79], v[228:231], v[102:105], v[64:79]
	ds_read_b128 v[224:227], v196 offset:49152
	ds_read_b128 v[228:231], v196 offset:57344
	s_waitcnt lgkmcnt(1)
	v_mfma_f32_32x32x16_bf16 v[80:95], v[224:227], v[98:101], v[80:95]
	v_mov_b32_e32 v224, v223
	s_nop 1
	v_permlane32_swap_b32_e32 v223, v224
	v_cvt_pk_bf16_f32 v226, v152, v153
	v_cvt_pk_bf16_f32 v227, v150, v151
	s_waitcnt lgkmcnt(0)
	v_mfma_f32_32x32x16_bf16 v[64:79], v[228:231], v[98:101], v[64:79]
	ds_read_b64_tr_b16 v[230:231], v184 offset:0
	ds_read_b64_tr_b16 v[232:233], v184 offset:0x800
	ds_read_b64_tr_b16 v[234:235], v184 offset:0x1000
	ds_read_b64_tr_b16 v[236:237], v184 offset:0x1800
	ds_read_b64_tr_b16 v[238:239], v184 offset:0x2000
	ds_read_b64_tr_b16 v[240:241], v184 offset:0x2800
	ds_read_b64_tr_b16 v[242:243], v184 offset:0x3000
	ds_read_b64_tr_b16 v[244:245], v184 offset:0x3800
	v_cvt_pk_bf16_f32 v228, v148, v149
	v_cvt_pk_bf16_f32 v229, v146, v147
	s_nop 0
	v_permlane32_swap_b32_e32 v226, v228
	v_permlane32_swap_b32_e32 v227, v229
	s_cmp_lt_u32 s0, s87
	s_cselect_b64 s[8:9], -1, 0
	s_and_b64 s[10:11], s[8:9], exec
	s_cselect_b32 s10, 0, s87
	s_cselect_b32 s11, s55, s51
	s_cselect_b32 s12, s54, s50
	s_sub_u32 s13, s0, s10
	s_subb_u32 s14, s1, 0
	s_and_b64 s[8:9], s[8:9], exec
	s_cselect_b32 s15, s86, 0x80
	s_cselect_b32 s16, s41, s47
	s_cselect_b32 s17, s40, s46
	s_lshl_b32 s56, s15, 6
	s_mul_i32 s8, s56, s14
	s_mul_hi_u32 s9, s56, s13
	s_add_i32 s9, s9, s8
	s_mul_i32 s8, s56, s13
	s_lshl_b64 s[8:9], s[8:9], 1
	s_add_u32 s8, s17, s8
	v_mul_lo_u32 v146, s15, v187
	s_addc_u32 s9, s16, s9
	v_or_b32_e32 v174, v146, v194
	v_lshl_add_u64 v[150:151], s[8:9], 0, v[174:175]
	v_lshl_add_u64 v[150:151], v[150:151], 0, s[56:57]
	global_load_dwordx4 v[146:149], v174, s[8:9]
	s_nop 0
	global_load_dwordx4 v[150:153], v[150:151], off
	s_lshl_b32 s8, s10, 14
	s_sub_u32 s8, 0, s8
	s_subb_u32 s9, 0, 0
	s_add_u32 s8, s12, s8
	s_addc_u32 s9, s11, s9
	v_lshl_add_u64 v[158:159], s[8:9], 0, v[180:181]
	v_add_co_u32_e32 v154, vcc, s75, v158
	s_nop 1
	v_addc_co_u32_e32 v155, vcc, -1, v159, vcc
	global_load_dwordx4 v[154:157], v[154:155], off
	s_nop 0
	global_load_dwordx4 v[158:161], v[158:159], off
	s_waitcnt lgkmcnt(0)
	s_nop 0
	v_mfma_f32_32x32x16_bf16 v[0:15], v[162:165], v[230:233], v[0:15]
	ds_read_b64_tr_b16 v[230:231], v184 offset:0x200
	ds_read_b64_tr_b16 v[232:233], v184 offset:0xa00
	v_mfma_f32_32x32x16_bf16 v[0:15], v[166:169], v[234:237], v[0:15]
	ds_read_b64_tr_b16 v[234:235], v184 offset:0x1200
	ds_read_b64_tr_b16 v[236:237], v184 offset:0x1a00
	v_mfma_f32_32x32x16_bf16 v[0:15], v[204:207], v[238:241], v[0:15]
	ds_read_b64_tr_b16 v[238:239], v184 offset:0x2200
	ds_read_b64_tr_b16 v[240:241], v184 offset:0x2a00
	v_mfma_f32_32x32x16_bf16 v[0:15], v[226:229], v[242:245], v[0:15]
	ds_read_b64_tr_b16 v[242:243], v184 offset:0x3200
	ds_read_b64_tr_b16 v[244:245], v184 offset:0x3a00
	s_waitcnt lgkmcnt(0)
	v_mfma_f32_32x32x16_bf16 v[48:63], v[162:165], v[230:233], v[48:63]
	ds_read_b64_tr_b16 v[230:231], v184 offset:0x400
	ds_read_b64_tr_b16 v[232:233], v184 offset:0xc00
	v_mfma_f32_32x32x16_bf16 v[48:63], v[166:169], v[234:237], v[48:63]
	ds_read_b64_tr_b16 v[234:235], v184 offset:0x1400
	ds_read_b64_tr_b16 v[236:237], v184 offset:0x1c00
	v_mfma_f32_32x32x16_bf16 v[48:63], v[204:207], v[238:241], v[48:63]
	ds_read_b64_tr_b16 v[238:239], v184 offset:0x2400
	ds_read_b64_tr_b16 v[240:241], v184 offset:0x2c00
	v_mfma_f32_32x32x16_bf16 v[48:63], v[226:229], v[242:245], v[48:63]
	ds_read_b64_tr_b16 v[242:243], v184 offset:0x3400
	ds_read_b64_tr_b16 v[244:245], v184 offset:0x3c00
	s_waitcnt lgkmcnt(0)
	v_mfma_f32_32x32x16_bf16 v[32:47], v[162:165], v[230:233], v[32:47]
	ds_read_b64_tr_b16 v[230:231], v184 offset:0x600
	ds_read_b64_tr_b16 v[232:233], v184 offset:0xe00
	v_mfma_f32_32x32x16_bf16 v[32:47], v[166:169], v[234:237], v[32:47]
	ds_read_b64_tr_b16 v[234:235], v184 offset:0x1600
	ds_read_b64_tr_b16 v[236:237], v184 offset:0x1e00
	v_mfma_f32_32x32x16_bf16 v[32:47], v[204:207], v[238:241], v[32:47]
	ds_read_b64_tr_b16 v[238:239], v184 offset:0x2600
	ds_read_b64_tr_b16 v[240:241], v184 offset:0x2e00
	v_mfma_f32_32x32x16_bf16 v[32:47], v[226:229], v[242:245], v[32:47]
	ds_read_b64_tr_b16 v[242:243], v184 offset:0x3600
	ds_read_b64_tr_b16 v[244:245], v184 offset:0x3e00
	s_waitcnt lgkmcnt(0)
	v_mfma_f32_32x32x16_bf16 v[16:31], v[162:165], v[230:233], v[16:31]
	v_max_f32_e32 v162, v81, v81
	v_max_f32_e32 v163, v80, v80
	v_max_f32_e32 v162, v163, v162
	v_max3_f32 v162, v162, v82, v83
	v_max3_f32 v162, v162, v84, v85
	v_max3_f32 v162, v162, v86, v87
	v_max3_f32 v162, v162, v88, v89
	v_max3_f32 v162, v162, v90, v91
	v_max3_f32 v162, v162, v92, v93
	v_mfma_f32_32x32x16_bf16 v[16:31], v[166:169], v[234:237], v[16:31]
	v_max3_f32 v162, v162, v94, v95
	v_max3_f32 v162, v162, v64, v65
	v_max3_f32 v162, v162, v66, v67
	v_max3_f32 v162, v162, v68, v69
	v_max3_f32 v162, v162, v70, v71
	v_max3_f32 v162, v162, v72, v73
	v_max3_f32 v162, v162, v74, v75
	v_max3_f32 v162, v162, v76, v77
	v_mfma_f32_32x32x16_bf16 v[16:31], v[204:207], v[238:241], v[16:31]
	v_max3_f32 v162, v162, v78, v79
	v_mov_b32_e32 v163, v162
	s_nop 1
	v_permlane32_swap_b32_e32 v162, v163
	v_max_f32_e32 v163, v163, v163
	v_max_f32_e32 v162, v162, v162
	v_max_f32_e32 v162, v162, v163
	v_sub_f32_e32 v163, v162, v170
	v_cmp_ge_f32_e32 vcc, s80, v163
	v_max_f32_e32 v163, v170, v170
	v_max_f32_e32 v162, v163, v162
	v_mfma_f32_32x32x16_bf16 v[16:31], v[226:229], v[242:245], v[16:31]
	v_sub_f32_e32 v163, v170, v162
	v_mul_f32_e32 v163, 0x3e0293ee, v163
	v_exp_f32_e32 v163, v163
	s_cmp_eq_u64 vcc, exec
	s_cselect_b64 s[8:9], -1, 0
	s_barrier
	s_waitcnt vmcnt(4)
	v_cndmask_b32_e64 v225, v163, 1.0, s[8:9]
	v_cmp_gt_f32_e32 vcc, 1.0, v225
	s_waitcnt vmcnt(7)
	ds_write_b128 v197, v[130:133]
	s_waitcnt vmcnt(6)
	ds_write_b128 v198, v[134:137]
	s_waitcnt vmcnt(5)
	ds_write_b128 v199, v[138:141] offset:32768
	s_waitcnt vmcnt(4)
	ds_write_b128 v200, v[142:145] offset:32768
	s_cbranch_vccz .LBB0_442
	s_and_saveexec_b64 s[10:11], s[6:7]
	ds_write_b32 v185, v225 offset:128
	s_or_b64 exec, exec, s[10:11]
	s_waitcnt lgkmcnt(0)
	v_add_u32_e32 v142, v182, v176
	ds_read_b128 v[130:133], v142 offset:224
	ds_read_b128 v[134:137], v142 offset:192
	ds_read_b128 v[138:141], v142 offset:160
	ds_read_b128 v[142:145], v142 offset:128
	s_waitcnt lgkmcnt(3)
	v_pk_mul_f32 v[12:13], v[12:13], v[130:131]
	s_waitcnt lgkmcnt(2)
	v_pk_mul_f32 v[8:9], v[8:9], v[134:135]
	s_waitcnt lgkmcnt(1)
	v_pk_mul_f32 v[4:5], v[4:5], v[138:139]
	v_pk_mul_f32 v[14:15], v[14:15], v[132:133]
	v_pk_mul_f32 v[10:11], v[10:11], v[136:137]
	v_pk_mul_f32 v[6:7], v[6:7], v[140:141]
	s_waitcnt lgkmcnt(0)
	v_pk_mul_f32 v[2:3], v[2:3], v[144:145]
	v_pk_mul_f32 v[0:1], v[0:1], v[142:143]
	v_pk_mul_f32 v[60:61], v[60:61], v[130:131]
	v_pk_mul_f32 v[56:57], v[56:57], v[134:135]
	v_pk_mul_f32 v[52:53], v[52:53], v[138:139]
	v_pk_mul_f32 v[62:63], v[62:63], v[132:133]
	v_pk_mul_f32 v[58:59], v[58:59], v[136:137]
	v_pk_mul_f32 v[54:55], v[54:55], v[140:141]
	v_pk_mul_f32 v[50:51], v[50:51], v[144:145]
	v_pk_mul_f32 v[48:49], v[48:49], v[142:143]
	v_pk_mul_f32 v[44:45], v[44:45], v[130:131]
	v_pk_mul_f32 v[40:41], v[40:41], v[134:135]
	v_pk_mul_f32 v[36:37], v[36:37], v[138:139]
	v_pk_mul_f32 v[46:47], v[46:47], v[132:133]
	v_pk_mul_f32 v[42:43], v[42:43], v[136:137]
	v_pk_mul_f32 v[38:39], v[38:39], v[140:141]
	v_pk_mul_f32 v[34:35], v[34:35], v[144:145]
	v_pk_mul_f32 v[32:33], v[32:33], v[142:143]
	v_pk_mul_f32 v[28:29], v[28:29], v[130:131]
	v_pk_mul_f32 v[24:25], v[24:25], v[134:135]
	v_pk_mul_f32 v[20:21], v[20:21], v[138:139]
	v_pk_mul_f32 v[30:31], v[30:31], v[132:133]
	v_pk_mul_f32 v[26:27], v[26:27], v[136:137]
	v_pk_mul_f32 v[22:23], v[22:23], v[140:141]
	v_pk_mul_f32 v[18:19], v[18:19], v[144:145]
	v_pk_mul_f32 v[16:17], v[16:17], v[142:143]
.LBB0_442:
	v_cndmask_b32_e64 v203, v162, v170, s[8:9]
	v_mul_f32_e32 v162, 0xbe0293ee, v203
	v_fmamk_f32 v80, v80, 0x3e0293ee, v162
	v_fmamk_f32 v81, v81, 0x3e0293ee, v162
	v_fmamk_f32 v82, v82, 0x3e0293ee, v162
	v_fmamk_f32 v83, v83, 0x3e0293ee, v162
	v_fmamk_f32 v84, v84, 0x3e0293ee, v162
	v_fmamk_f32 v85, v85, 0x3e0293ee, v162
	v_fmamk_f32 v86, v86, 0x3e0293ee, v162
	v_fmamk_f32 v87, v87, 0x3e0293ee, v162
	v_fmamk_f32 v88, v88, 0x3e0293ee, v162
	v_fmamk_f32 v89, v89, 0x3e0293ee, v162
	v_fmamk_f32 v90, v90, 0x3e0293ee, v162
	v_fmamk_f32 v91, v91, 0x3e0293ee, v162
	v_fmamk_f32 v92, v92, 0x3e0293ee, v162
	v_fmamk_f32 v93, v93, 0x3e0293ee, v162
	v_fmamk_f32 v94, v94, 0x3e0293ee, v162
	v_fmamk_f32 v95, v95, 0x3e0293ee, v162
	v_exp_f32_e32 v143, v80
	v_exp_f32_e32 v145, v81
	v_exp_f32_e32 v141, v82
	v_exp_f32_e32 v144, v83
	v_exp_f32_e32 v140, v84
	v_exp_f32_e32 v142, v85
	v_exp_f32_e32 v138, v86
	v_exp_f32_e32 v139, v87
	v_exp_f32_e32 v135, v88
	v_exp_f32_e32 v137, v89
	v_exp_f32_e32 v134, v90
	v_exp_f32_e32 v136, v91
	v_exp_f32_e32 v131, v92
	v_exp_f32_e32 v133, v93
	v_exp_f32_e32 v130, v94
	v_exp_f32_e32 v132, v95
	v_fmamk_f32 v171, v64, 0x3e0293ee, v162
	v_fmamk_f32 v172, v65, 0x3e0293ee, v162
	v_fmamk_f32 v173, v66, 0x3e0293ee, v162
	v_fmamk_f32 v174, v67, 0x3e0293ee, v162
	v_fmamk_f32 v204, v68, 0x3e0293ee, v162
	v_fmamk_f32 v164, v69, 0x3e0293ee, v162
	v_fmamk_f32 v165, v70, 0x3e0293ee, v162
	v_fmamk_f32 v166, v71, 0x3e0293ee, v162
	v_fmamk_f32 v167, v72, 0x3e0293ee, v162
	v_fmamk_f32 v168, v73, 0x3e0293ee, v162
	v_fmamk_f32 v169, v74, 0x3e0293ee, v162
	v_fmamk_f32 v170, v75, 0x3e0293ee, v162
	v_fmamk_f32 v163, v76, 0x3e0293ee, v162
	v_fmamk_f32 v205, v77, 0x3e0293ee, v162
	v_fmamk_f32 v206, v78, 0x3e0293ee, v162
	v_fmac_f32_e32 v162, 0x3e0293ee, v79
	s_waitcnt lgkmcnt(0)
	s_barrier
	ds_read_b128 v[64:67], v188 offset:32768
	ds_read_b128 v[68:71], v188 offset:40960
	ds_read_b128 v[226:229], v189 offset:32768
	ds_read_b128 v[230:233], v189 offset:40960
	v_exp_f32_e32 v236, v162
	v_add_f32_e32 v162, 0, v143
	s_waitcnt lgkmcnt(3)
	v_mfma_f32_32x32x16_bf16 v[80:95], v[64:67], v[126:129], 0
	v_add_f32_e32 v162, v145, v162
	v_add_f32_e32 v162, v141, v162
	v_add_f32_e32 v162, v144, v162
	v_add_f32_e32 v162, v140, v162
	v_add_f32_e32 v162, v142, v162
	v_add_f32_e32 v162, v138, v162
	v_add_f32_e32 v162, v139, v162
	s_waitcnt lgkmcnt(2)
	v_mfma_f32_32x32x16_bf16 v[64:79], v[68:71], v[126:129], 0
	v_add_f32_e32 v162, v135, v162
	v_add_f32_e32 v162, v137, v162
	v_add_f32_e32 v162, v134, v162
	v_add_f32_e32 v162, v136, v162
	v_exp_f32_e32 v171, v171
	v_add_f32_e32 v162, v131, v162
	v_exp_f32_e32 v172, v172
	s_waitcnt lgkmcnt(1)
	v_mfma_f32_32x32x16_bf16 v[80:95], v[226:229], v[122:125], v[80:95]
	v_add_f32_e32 v162, v133, v162
	v_exp_f32_e32 v173, v173
	v_add_f32_e32 v162, v130, v162
	v_exp_f32_e32 v174, v174
	v_add_f32_e32 v162, v132, v162
	v_exp_f32_e32 v204, v204
	v_add_f32_e32 v162, v171, v162
	s_waitcnt lgkmcnt(0)
	v_mfma_f32_32x32x16_bf16 v[64:79], v[230:233], v[122:125], v[64:79]
	ds_read_b128 v[226:229], v190 offset:32768
	ds_read_b128 v[230:233], v190 offset:40960
	v_exp_f32_e32 v207, v164
	v_add_f32_e32 v162, v172, v162
	v_exp_f32_e32 v222, v165
	v_add_f32_e32 v162, v173, v162
	v_add_f32_e32 v162, v174, v162
	v_add_f32_e32 v162, v204, v162
	s_waitcnt lgkmcnt(1)
	v_mfma_f32_32x32x16_bf16 v[80:95], v[226:229], v[118:121], v[80:95]
	v_add_f32_e32 v162, v207, v162
	v_add_f32_e32 v162, v222, v162
	v_exp_f32_e32 v234, v205
	v_exp_f32_e32 v235, v206
	v_cvt_pk_bf16_f32 v164, v140, v142
	v_cvt_pk_bf16_f32 v165, v138, v139
	s_waitcnt lgkmcnt(0)
	v_mfma_f32_32x32x16_bf16 v[64:79], v[230:233], v[118:121], v[64:79]
	ds_read_b128 v[226:229], v191 offset:32768
	ds_read_b128 v[230:233], v191 offset:40960
	s_waitcnt lgkmcnt(1)
	v_mfma_f32_32x32x16_bf16 v[80:95], v[226:229], v[114:117], v[80:95]
	s_waitcnt lgkmcnt(0)
	v_mfma_f32_32x32x16_bf16 v[64:79], v[230:233], v[114:117], v[64:79]
	ds_read_b128 v[226:229], v192 offset:32768
	ds_read_b128 v[230:233], v192 offset:40960
	s_waitcnt lgkmcnt(1)
	v_mfma_f32_32x32x16_bf16 v[80:95], v[226:229], v[110:113], v[80:95]
	s_waitcnt lgkmcnt(0)
	v_mfma_f32_32x32x16_bf16 v[64:79], v[230:233], v[110:113], v[64:79]
	ds_read_b128 v[226:229], v193 offset:32768
	ds_read_b128 v[230:233], v193 offset:40960
	s_waitcnt lgkmcnt(1)
	v_mfma_f32_32x32x16_bf16 v[80:95], v[226:229], v[106:109], v[80:95]
	s_waitcnt lgkmcnt(0)
	v_mfma_f32_32x32x16_bf16 v[64:79], v[230:233], v[106:109], v[64:79]
	ds_read_b128 v[226:229], v195 offset:32768
	ds_read_b128 v[230:233], v195 offset:40960
	s_waitcnt lgkmcnt(1)
	v_mfma_f32_32x32x16_bf16 v[80:95], v[226:229], v[102:105], v[80:95]
	s_waitcnt lgkmcnt(0)
	v_mfma_f32_32x32x16_bf16 v[64:79], v[230:233], v[102:105], v[64:79]
	ds_read_b128 v[226:229], v196 offset:32768
	ds_read_b128 v[230:233], v196 offset:40960
	s_waitcnt lgkmcnt(1)
	v_mfma_f32_32x32x16_bf16 v[80:95], v[226:229], v[98:101], v[80:95]
	v_exp_f32_e32 v228, v166
	v_exp_f32_e32 v229, v167
	v_cvt_pk_bf16_f32 v166, v135, v137
	v_cvt_pk_bf16_f32 v167, v134, v136
	v_add_f32_e32 v162, v228, v162
	v_add_f32_e32 v162, v229, v162
	s_waitcnt lgkmcnt(0)
	v_mfma_f32_32x32x16_bf16 v[64:79], v[230:233], v[98:101], v[64:79]
	v_exp_f32_e32 v230, v168
	v_exp_f32_e32 v231, v169
	v_exp_f32_e32 v232, v170
	v_exp_f32_e32 v233, v163
	v_add_f32_e32 v162, v230, v162
	v_add_f32_e32 v162, v231, v162
	v_add_f32_e32 v162, v232, v162
	v_add_f32_e32 v162, v233, v162
	v_add_f32_e32 v162, v234, v162
	v_add_f32_e32 v162, v235, v162
	v_add_f32_e32 v226, v236, v162
	v_mov_b32_e32 v227, v226
	v_cvt_pk_bf16_f32 v162, v143, v145
	v_cvt_pk_bf16_f32 v163, v141, v144
	s_nop 1
	v_permlane32_swap_b32_e32 v226, v227
	v_permlane32_swap_b32_e32 v162, v164
	v_permlane32_swap_b32_e32 v163, v165
	v_cvt_pk_bf16_f32 v168, v131, v133
	v_cvt_pk_bf16_f32 v169, v130, v132
	v_cvt_pk_bf16_f32 v170, v171, v172
	v_cvt_pk_bf16_f32 v171, v173, v174
	v_cvt_pk_bf16_f32 v172, v204, v207
	v_cvt_pk_bf16_f32 v173, v222, v228
	v_cvt_pk_bf16_f32 v204, v229, v230
	v_cvt_pk_bf16_f32 v205, v231, v232
	v_cvt_pk_bf16_f32 v206, v233, v234
	v_cvt_pk_bf16_f32 v207, v235, v236
	ds_read_b64_tr_b16 v[228:229], v202 offset:0
	ds_read_b64_tr_b16 v[230:231], v202 offset:0x800
	ds_read_b64_tr_b16 v[232:233], v202 offset:0x1000
	ds_read_b64_tr_b16 v[234:235], v202 offset:0x1800
	ds_read_b64_tr_b16 v[236:237], v202 offset:0x2000
	ds_read_b64_tr_b16 v[238:239], v202 offset:0x2800
	ds_read_b64_tr_b16 v[240:241], v202 offset:0x3000
	ds_read_b64_tr_b16 v[242:243], v202 offset:0x3800
	s_nop 0
	v_permlane32_swap_b32_e32 v166, v168
	v_permlane32_swap_b32_e32 v167, v169
	v_permlane32_swap_b32_e32 v170, v172
	v_permlane32_swap_b32_e32 v171, v173
	v_permlane32_swap_b32_e32 v204, v206
	v_permlane32_swap_b32_e32 v205, v207
	s_add_i32 s8, s0, 1
	s_min_i32 s12, s8, s4
	s_cmp_lt_i32 s12, s87
	s_cselect_b64 s[8:9], -1, 0
	s_and_b64 s[10:11], s[8:9], exec
	s_cselect_b32 s10, 0, s87
	s_sub_i32 s10, s12, s10
	s_and_b64 s[12:13], s[8:9], exec
	s_cselect_b32 s14, s55, s51
	s_cselect_b32 s15, s54, s50
	s_ashr_i32 s11, s10, 31
	s_lshl_b64 s[12:13], s[10:11], 14
	s_add_u32 s12, s15, s12
	s_addc_u32 s13, s14, s13
	s_and_b64 s[8:9], s[8:9], exec
	s_cselect_b32 s11, s86, 0x80
	s_cselect_b32 s14, s41, s47
	s_cselect_b32 s15, s40, s46
	s_lshl_b32 s56, s11, 6
	s_mul_hi_i32 s9, s56, s10
	s_mul_i32 s8, s56, s10
	s_lshl_b64 s[8:9], s[8:9], 1
	s_add_u32 s8, s15, s8
	v_mul_lo_u32 v130, s11, v187
	s_addc_u32 s9, s14, s9
	v_or_b32_e32 v174, v130, v194
	v_lshl_add_u64 v[138:139], s[12:13], 0, v[178:179]
	v_lshl_add_u64 v[134:135], s[8:9], 0, v[174:175]
	v_add_co_u32_e32 v142, vcc, s73, v138
	v_lshl_add_u64 v[134:135], v[134:135], 0, s[56:57]
	s_nop 0
	v_addc_co_u32_e32 v143, vcc, 0, v139, vcc
	global_load_dwordx4 v[130:133], v174, s[8:9]
	s_nop 0
	global_load_dwordx4 v[134:137], v[134:135], off
	s_nop 0
	global_load_dwordx4 v[138:141], v[138:139], off
	s_nop 0
	global_load_dwordx4 v[142:145], v[142:143], off
	s_waitcnt lgkmcnt(0)
	s_nop 0
	v_mfma_f32_32x32x16_bf16 v[0:15], v[162:165], v[228:231], v[0:15]
	ds_read_b64_tr_b16 v[228:229], v202 offset:0x200
	ds_read_b64_tr_b16 v[230:231], v202 offset:0xa00
	v_mfma_f32_32x32x16_bf16 v[0:15], v[166:169], v[232:235], v[0:15]
	ds_read_b64_tr_b16 v[232:233], v202 offset:0x1200
	ds_read_b64_tr_b16 v[234:235], v202 offset:0x1a00
	v_mfma_f32_32x32x16_bf16 v[0:15], v[170:173], v[236:239], v[0:15]
	ds_read_b64_tr_b16 v[236:237], v202 offset:0x2200
	ds_read_b64_tr_b16 v[238:239], v202 offset:0x2a00
	v_mfma_f32_32x32x16_bf16 v[0:15], v[204:207], v[240:243], v[0:15]
	ds_read_b64_tr_b16 v[240:241], v202 offset:0x3200
	ds_read_b64_tr_b16 v[242:243], v202 offset:0x3a00
	s_waitcnt lgkmcnt(0)
	v_mfma_f32_32x32x16_bf16 v[48:63], v[162:165], v[228:231], v[48:63]
	ds_read_b64_tr_b16 v[228:229], v202 offset:0x400
	ds_read_b64_tr_b16 v[230:231], v202 offset:0xc00
	v_mfma_f32_32x32x16_bf16 v[48:63], v[166:169], v[232:235], v[48:63]
	ds_read_b64_tr_b16 v[232:233], v202 offset:0x1400
	ds_read_b64_tr_b16 v[234:235], v202 offset:0x1c00
	v_mfma_f32_32x32x16_bf16 v[48:63], v[170:173], v[236:239], v[48:63]
	ds_read_b64_tr_b16 v[236:237], v202 offset:0x2400
	ds_read_b64_tr_b16 v[238:239], v202 offset:0x2c00
	v_mfma_f32_32x32x16_bf16 v[48:63], v[204:207], v[240:243], v[48:63]
	ds_read_b64_tr_b16 v[240:241], v202 offset:0x3400
	ds_read_b64_tr_b16 v[242:243], v202 offset:0x3c00
	s_waitcnt lgkmcnt(0)
	v_mfma_f32_32x32x16_bf16 v[32:47], v[162:165], v[228:231], v[32:47]
	ds_read_b64_tr_b16 v[228:229], v202 offset:0x600
	ds_read_b64_tr_b16 v[230:231], v202 offset:0xe00
	v_mfma_f32_32x32x16_bf16 v[32:47], v[166:169], v[232:235], v[32:47]
	ds_read_b64_tr_b16 v[232:233], v202 offset:0x1600
	ds_read_b64_tr_b16 v[234:235], v202 offset:0x1e00
	v_mfma_f32_32x32x16_bf16 v[32:47], v[170:173], v[236:239], v[32:47]
	ds_read_b64_tr_b16 v[236:237], v202 offset:0x2600
	ds_read_b64_tr_b16 v[238:239], v202 offset:0x2e00
	v_mfma_f32_32x32x16_bf16 v[32:47], v[204:207], v[240:243], v[32:47]
	ds_read_b64_tr_b16 v[240:241], v202 offset:0x3600
	ds_read_b64_tr_b16 v[242:243], v202 offset:0x3e00
	s_waitcnt lgkmcnt(0)
	v_mfma_f32_32x32x16_bf16 v[16:31], v[162:165], v[228:231], v[16:31]
	v_max_f32_e32 v162, v81, v81
	v_max_f32_e32 v163, v80, v80
	v_max_f32_e32 v162, v163, v162
	v_max3_f32 v162, v162, v82, v83
	v_max3_f32 v162, v162, v84, v85
	v_max3_f32 v162, v162, v86, v87
	v_max3_f32 v162, v162, v88, v89
	v_max3_f32 v162, v162, v90, v91
	v_max3_f32 v162, v162, v92, v93
	v_mfma_f32_32x32x16_bf16 v[16:31], v[166:169], v[232:235], v[16:31]
	v_max3_f32 v162, v162, v94, v95
	v_max3_f32 v162, v162, v64, v65
	v_max3_f32 v162, v162, v66, v67
	v_max3_f32 v162, v162, v68, v69
	v_max3_f32 v162, v162, v70, v71
	v_max3_f32 v162, v162, v72, v73
	v_max3_f32 v162, v162, v74, v75
	v_max3_f32 v162, v162, v76, v77
	v_mfma_f32_32x32x16_bf16 v[16:31], v[170:173], v[236:239], v[16:31]
	v_max3_f32 v162, v162, v78, v79
	v_mov_b32_e32 v163, v162
	s_nop 1
	v_permlane32_swap_b32_e32 v162, v163
	v_max_f32_e32 v163, v163, v163
	v_max_f32_e32 v162, v162, v162
	v_max_f32_e32 v162, v162, v163
	v_sub_f32_e32 v163, v162, v203
	v_cmp_ge_f32_e32 vcc, s80, v163
	v_max_f32_e32 v163, v203, v203
	v_max_f32_e32 v163, v163, v162
	v_mfma_f32_32x32x16_bf16 v[16:31], v[204:207], v[240:243], v[16:31]
	v_sub_f32_e32 v162, v203, v163
	v_mul_f32_e32 v162, 0x3e0293ee, v162
	v_exp_f32_e32 v162, v162
	s_cmp_eq_u64 vcc, exec
	s_cselect_b64 s[8:9], -1, 0
	s_barrier
	s_waitcnt vmcnt(4)
	v_cndmask_b32_e64 v162, v162, 1.0, s[8:9]
	v_cmp_gt_f32_e32 vcc, 1.0, v162
	s_waitcnt vmcnt(7)
	ds_write_b128 v197, v[146:149] offset:16384
	s_waitcnt vmcnt(6)
	ds_write_b128 v198, v[150:153] offset:16384
	s_waitcnt vmcnt(5)
	ds_write_b128 v199, v[154:157] offset:49152
	s_waitcnt vmcnt(4)
	ds_write_b128 v200, v[158:161] offset:49152
	s_cbranch_vccz .LBB0_446
	s_and_saveexec_b64 s[10:11], s[6:7]
	ds_write_b32 v185, v162 offset:128
	s_or_b64 exec, exec, s[10:11]
	s_waitcnt lgkmcnt(0)
	v_add_u32_e32 v158, v182, v176
	ds_read_b128 v[146:149], v158 offset:224
	ds_read_b128 v[150:153], v158 offset:192
	ds_read_b128 v[154:157], v158 offset:128
	ds_read_b128 v[158:161], v158 offset:160
	s_waitcnt lgkmcnt(3)
	v_pk_mul_f32 v[14:15], v[14:15], v[148:149]
	v_pk_mul_f32 v[12:13], v[12:13], v[146:147]
	s_waitcnt lgkmcnt(2)
	v_pk_mul_f32 v[10:11], v[10:11], v[152:153]
	v_pk_mul_f32 v[8:9], v[8:9], v[150:151]
	s_waitcnt lgkmcnt(0)
	v_pk_mul_f32 v[6:7], v[6:7], v[160:161]
	v_pk_mul_f32 v[4:5], v[4:5], v[158:159]
	v_pk_mul_f32 v[2:3], v[2:3], v[156:157]
	v_pk_mul_f32 v[0:1], v[0:1], v[154:155]
	v_pk_mul_f32 v[62:63], v[62:63], v[148:149]
	v_pk_mul_f32 v[60:61], v[60:61], v[146:147]
	v_pk_mul_f32 v[58:59], v[58:59], v[152:153]
	v_pk_mul_f32 v[56:57], v[56:57], v[150:151]
	v_pk_mul_f32 v[54:55], v[54:55], v[160:161]
	v_pk_mul_f32 v[52:53], v[52:53], v[158:159]
	v_pk_mul_f32 v[50:51], v[50:51], v[156:157]
	v_pk_mul_f32 v[48:49], v[48:49], v[154:155]
	v_pk_mul_f32 v[46:47], v[46:47], v[148:149]
	v_pk_mul_f32 v[44:45], v[44:45], v[146:147]
	v_pk_mul_f32 v[42:43], v[42:43], v[152:153]
	v_pk_mul_f32 v[40:41], v[40:41], v[150:151]
	v_pk_mul_f32 v[38:39], v[38:39], v[160:161]
	v_pk_mul_f32 v[36:37], v[36:37], v[158:159]
	v_pk_mul_f32 v[34:35], v[34:35], v[156:157]
	v_pk_mul_f32 v[32:33], v[32:33], v[154:155]
	v_pk_mul_f32 v[30:31], v[30:31], v[148:149]
	v_pk_mul_f32 v[28:29], v[28:29], v[146:147]
	v_pk_mul_f32 v[26:27], v[26:27], v[152:153]
	v_pk_mul_f32 v[24:25], v[24:25], v[150:151]
	v_pk_mul_f32 v[22:23], v[22:23], v[160:161]
	v_pk_mul_f32 v[20:21], v[20:21], v[158:159]
	v_pk_mul_f32 v[18:19], v[18:19], v[156:157]
	v_pk_mul_f32 v[16:17], v[16:17], v[154:155]
